# attention rpb bias loads: 16 serialized exec-masked loads per step replaced by clamped loads issued together ahead of K/V loads
# speedup vs baseline: 1.0166x; 1.0166x over previous
.LBB0_281:
	s_lshr_b32 s0, s34, 1
	s_and_b32 s6, s0, 30
	s_ashr_i32 s4, s34, 9
	s_lshl_b32 s5, s4, 11
	s_lshl_b32 s1, s6, 6
	s_or_b32 s7, s1, s5
	s_lshl_b32 s1, s34, 4
	s_and_b32 s1, s1, 48
	s_or_b32 s7, s7, s1
	s_bfe_u32 s0, s34, 0x30006
	v_or_b32_e32 v184, s7, v192
	v_mov_b64_e32 v[30:31], s[50:51]
	v_mad_i64_i32 v[186:187], s[8:9], v184, s37, v[30:31]
	s_lshl_b32 s42, s0, 8
	v_lshl_add_u64 v[2:3], v[186:187], 0, s[42:43]
	v_lshlrev_b32_e32 v194, 1, v170
	v_lshl_add_u64 v[6:7], v[2:3], 0, v[194:195]
	v_add_co_u32_e32 v2, vcc, s91, v6
	v_lshl_add_u64 v[14:15], v[6:7], 0, s[10:11]
	s_nop 0
	v_addc_co_u32_e32 v3, vcc, 0, v7, vcc
	global_load_dwordx4 v[2:5], v[2:3], off
	s_nop 0
	global_load_dwordx4 v[6:9], v[14:15], off offset:64
	global_load_dwordx4 v[10:13], v[14:15], off offset:128
	global_load_dwordx4 v[18:21], v[14:15], off offset:192
	global_load_dwordx4 v[22:25], v[176:177], off offset:16
	global_load_dwordx4 v[26:29], v[176:177], off
	v_or_b32_e32 v180, 64, v184
	v_mad_i64_i32 v[182:183], s[8:9], v180, s37, v[30:31]
	v_sub_u32_e64 v111, s6, 3 clamp
	v_sub_u32_e64 v112, s6, 4 clamp
	v_readfirstlane_b32 s6, v111
	v_readfirstlane_b32 s7, v112
	s_min_u32 s14, s6, 24
	s_min_u32 s15, s7, 24
	s_sub_i32 s59, s14, s15
	s_lshl_b32 s13, s0, 7
	s_add_i32 s2, s59, 8
	s_cmp_lt_i32 s2, -7
	s_waitcnt vmcnt(0)
	v_lshlrev_b32_e32 v42, 16, v6
	v_and_b32_e32 v43, 0xffff0000, v6
	v_and_b32_e32 v16, 0xffff0000, v18
	v_and_b32_e32 v35, 0xffff0000, v2
	v_lshlrev_b32_e32 v34, 16, v2
	v_lshlrev_b32_e32 v17, 16, v18
	v_mul_f32_e32 v18, v35, v35
	v_lshlrev_b32_e32 v36, 16, v3
	v_fmac_f32_e32 v18, v34, v34
	v_and_b32_e32 v37, 0xffff0000, v3
	v_fmac_f32_e32 v18, v36, v36
	v_lshlrev_b32_e32 v38, 16, v4
	v_fmac_f32_e32 v18, v37, v37
	v_and_b32_e32 v39, 0xffff0000, v4
	v_fmac_f32_e32 v18, v38, v38
	v_lshlrev_b32_e32 v40, 16, v5
	v_fmac_f32_e32 v18, v39, v39
	v_and_b32_e32 v41, 0xffff0000, v5
	v_fmac_f32_e32 v18, v40, v40
	v_fmac_f32_e32 v18, v41, v41
	v_fmac_f32_e32 v18, v42, v42
	v_lshlrev_b32_e32 v44, 16, v7
	v_fmac_f32_e32 v18, v43, v43
	v_and_b32_e32 v45, 0xffff0000, v7
	v_fmac_f32_e32 v18, v44, v44
	v_lshlrev_b32_e32 v46, 16, v8
	v_fmac_f32_e32 v18, v45, v45
	v_and_b32_e32 v47, 0xffff0000, v8
	v_fmac_f32_e32 v18, v46, v46
	v_lshlrev_b32_e32 v48, 16, v9
	v_fmac_f32_e32 v18, v47, v47
	v_and_b32_e32 v49, 0xffff0000, v9
	v_fmac_f32_e32 v18, v48, v48
	v_lshlrev_b32_e32 v58, 16, v10
	v_fmac_f32_e32 v18, v49, v49
	v_and_b32_e32 v59, 0xffff0000, v10
	v_fmac_f32_e32 v18, v58, v58
	v_lshlrev_b32_e32 v60, 16, v11
	v_fmac_f32_e32 v18, v59, v59
	v_and_b32_e32 v61, 0xffff0000, v11
	v_fmac_f32_e32 v18, v60, v60
	v_lshlrev_b32_e32 v62, 16, v12
	v_fmac_f32_e32 v18, v61, v61
	v_and_b32_e32 v63, 0xffff0000, v12
	v_fmac_f32_e32 v18, v62, v62
	v_lshlrev_b32_e32 v64, 16, v13
	v_fmac_f32_e32 v18, v63, v63
	v_and_b32_e32 v65, 0xffff0000, v13
	v_fmac_f32_e32 v18, v64, v64
	v_pk_mul_f32 v[2:3], v[16:17], v[16:17]
	v_fmac_f32_e32 v18, v65, v65
	v_and_b32_e32 v14, 0xffff0000, v19
	v_lshlrev_b32_e32 v15, 16, v19
	v_add_f32_e32 v3, v3, v18
	v_pk_mul_f32 v[4:5], v[14:15], v[14:15]
	v_add_f32_e32 v2, v2, v3
	v_and_b32_e32 v12, 0xffff0000, v20
	v_lshlrev_b32_e32 v13, 16, v20
	v_add_f32_e32 v2, v5, v2
	v_pk_mul_f32 v[6:7], v[12:13], v[12:13]
	v_add_f32_e32 v2, v4, v2
	v_and_b32_e32 v10, 0xffff0000, v21
	v_lshlrev_b32_e32 v11, 16, v21
	v_add_f32_e32 v2, v7, v2
	v_pk_mul_f32 v[8:9], v[10:11], v[10:11]
	v_add_f32_e32 v2, v6, v2
	v_add_f32_e32 v2, v9, v2
	v_add_f32_e32 v6, v8, v2
	ds_bpermute_b32 v7, v171, v6
	v_lshl_add_u64 v[2:3], v[182:183], 0, s[42:43]
	v_lshl_add_u64 v[2:3], v[2:3], 0, v[194:195]
	v_lshl_add_u64 v[4:5], v[2:3], 0, s[10:11]
	v_add_co_u32_e32 v2, vcc, s91, v2
	s_waitcnt lgkmcnt(0)
	v_add_f32_e32 v6, v6, v7
	ds_bpermute_b32 v7, v199, v6
	v_addc_co_u32_e32 v3, vcc, 0, v3, vcc
	s_waitcnt lgkmcnt(0)
	v_add_f32_e32 v6, v6, v7
	v_fmamk_f32 v6, v6, 0x3c000000, v230
	v_mul_f32_e32 v7, 0x4b800000, v6
	v_cmp_gt_f32_e32 vcc, s70, v6
	s_nop 1
	v_cndmask_b32_e32 v6, v6, v7, vcc
	v_rsq_f32_e32 v50, v6
	global_load_dwordx4 v[18:21], v[4:5], off offset:64
	global_load_dwordx4 v[6:9], v[4:5], off offset:128
	global_load_dwordx4 v[30:33], v[2:3], off
	s_nop 0
	global_load_dwordx4 v[2:5], v[4:5], off offset:192
	v_mul_f32_e32 v51, 0x45800000, v50
	v_cndmask_b32_e32 v50, v50, v51, vcc
	v_mul_f32_e32 v66, 0x3db504f3, v50
	v_mul_f32_e32 v34, v66, v34
	v_mul_f32_e32 v35, v66, v35
	v_mul_f32_e32 v36, v66, v36
	v_mul_f32_e32 v37, v66, v37
	v_mul_f32_e32 v38, v66, v38
	v_mul_f32_e32 v39, v66, v39
	v_mul_f32_e32 v40, v66, v40
	v_mul_f32_e32 v41, v66, v41
	v_mul_f32_e32 v26, v26, v34
	v_mul_f32_e32 v27, v27, v35
	v_mul_f32_e32 v28, v28, v36
	v_mul_f32_e32 v29, v29, v37
	v_mul_f32_e32 v22, v22, v38
	v_mul_f32_e32 v23, v23, v39
	v_mul_f32_e32 v24, v24, v40
	v_mul_f32_e32 v25, v25, v41
	v_cvt_pk_bf16_f32 v50, v26, v27
	v_cvt_pk_bf16_f32 v51, v28, v29
	v_cvt_pk_bf16_f32 v52, v22, v23
	v_cvt_pk_bf16_f32 v53, v24, v25
	global_load_dwordx4 v[22:25], v[176:177], off offset:128
	global_load_dwordx4 v[26:29], v[176:177], off offset:144
	v_mul_f32_e32 v34, v66, v42
	v_mul_f32_e32 v35, v66, v43
	v_mul_f32_e32 v36, v66, v44
	v_mul_f32_e32 v37, v66, v45
	v_mul_f32_e32 v38, v66, v46
	v_mul_f32_e32 v39, v66, v47
	v_mul_f32_e32 v40, v66, v48
	v_mul_f32_e32 v41, v66, v49
	v_mul_f32_e32 v15, v66, v15
	v_mul_f32_e32 v14, v66, v14
	v_mul_f32_e32 v13, v66, v13
	v_mul_f32_e32 v12, v66, v12
	v_mul_f32_e32 v11, v66, v11
	v_mul_f32_e32 v10, v66, v10
	s_waitcnt vmcnt(4)
	v_lshlrev_b32_e32 v42, 16, v6
	v_and_b32_e32 v43, 0xffff0000, v6
	v_lshlrev_b32_e32 v44, 16, v7
	v_and_b32_e32 v45, 0xffff0000, v7
	v_mul_f32_e32 v6, v66, v17
	v_mul_f32_e32 v7, v66, v16
	s_waitcnt vmcnt(2)
	v_and_b32_e32 v98, 0xffff0000, v2
	v_lshlrev_b32_e32 v99, 16, v2
	v_and_b32_e32 v96, 0xffff0000, v3
	v_lshlrev_b32_e32 v97, 16, v3
	v_pk_mul_f32 v[2:3], v[98:99], v[98:99]
	v_and_b32_e32 v94, 0xffff0000, v4
	v_lshlrev_b32_e32 v95, 16, v4
	v_and_b32_e32 v100, 0xffff0000, v5
	v_lshlrev_b32_e32 v101, 16, v5
	v_pk_mul_f32 v[4:5], v[96:97], v[96:97]
	s_waitcnt vmcnt(1)
	v_mul_f32_e32 v22, v22, v34
	v_mul_f32_e32 v23, v23, v35
	v_mul_f32_e32 v24, v24, v36
	v_mul_f32_e32 v25, v25, v37
	s_waitcnt vmcnt(0)
	v_mul_f32_e32 v26, v26, v38
	v_mul_f32_e32 v27, v27, v39
	v_mul_f32_e32 v28, v28, v40
	v_mul_f32_e32 v29, v29, v41
	v_cvt_pk_bf16_f32 v54, v22, v23
	v_cvt_pk_bf16_f32 v55, v24, v25
	v_cvt_pk_bf16_f32 v56, v26, v27
	v_cvt_pk_bf16_f32 v57, v28, v29
	global_load_dwordx4 v[22:25], v[176:177], off offset:256
	global_load_dwordx4 v[26:29], v[176:177], off offset:272
	v_mul_f32_e32 v34, v66, v58
	v_mul_f32_e32 v35, v66, v59
	v_mul_f32_e32 v36, v66, v60
	v_mul_f32_e32 v37, v66, v61
	v_mul_f32_e32 v38, v66, v62
	v_mul_f32_e32 v39, v66, v63
	v_mul_f32_e32 v40, v66, v64
	v_mul_f32_e32 v41, v66, v65
	s_waitcnt vmcnt(1)
	v_mul_f32_e32 v22, v22, v34
	v_mul_f32_e32 v23, v23, v35
	v_mul_f32_e32 v24, v24, v36
	v_mul_f32_e32 v25, v25, v37
	s_waitcnt vmcnt(0)
	v_mul_f32_e32 v26, v26, v38
	v_mul_f32_e32 v27, v27, v39
	v_mul_f32_e32 v28, v28, v40
	v_mul_f32_e32 v29, v29, v41
	v_cvt_pk_bf16_f32 v58, v22, v23
	v_cvt_pk_bf16_f32 v59, v24, v25
	v_cvt_pk_bf16_f32 v60, v26, v27
	v_cvt_pk_bf16_f32 v61, v28, v29
	global_load_dwordx4 v[22:25], v[176:177], off offset:384
	global_load_dwordx4 v[26:29], v[176:177], off offset:400
	v_lshlrev_b32_e32 v34, 16, v30
	v_and_b32_e32 v30, 0xffff0000, v30
	v_lshlrev_b32_e32 v35, 16, v31
	v_and_b32_e32 v31, 0xffff0000, v31
	v_lshlrev_b32_e32 v36, 16, v32
	v_and_b32_e32 v32, 0xffff0000, v32
	v_lshlrev_b32_e32 v37, 16, v33
	v_and_b32_e32 v33, 0xffff0000, v33
	v_lshlrev_b32_e32 v38, 16, v18
	v_and_b32_e32 v18, 0xffff0000, v18
	v_lshlrev_b32_e32 v39, 16, v19
	v_and_b32_e32 v19, 0xffff0000, v19
	v_lshlrev_b32_e32 v40, 16, v20
	v_and_b32_e32 v20, 0xffff0000, v20
	v_lshlrev_b32_e32 v41, 16, v21
	v_and_b32_e32 v21, 0xffff0000, v21
	s_waitcnt vmcnt(1)
	v_mul_f32_e32 v15, v24, v15
	v_mul_f32_e32 v14, v25, v14
	s_waitcnt vmcnt(0)
	v_mul_f32_e32 v13, v26, v13
	v_mul_f32_e32 v12, v27, v12
	v_mul_f32_e32 v11, v28, v11
	v_mul_f32_e32 v10, v29, v10
	v_mul_f32_e32 v6, v22, v6
	v_mul_f32_e32 v7, v23, v7
	v_cvt_pk_bf16_f32 v66, v6, v7
	v_cvt_pk_bf16_f32 v67, v15, v14
	v_cvt_pk_bf16_f32 v68, v13, v12
	v_cvt_pk_bf16_f32 v69, v11, v10
	global_load_dwordx4 v[10:13], v[176:177], off offset:16
	global_load_dwordx4 v[14:17], v[176:177], off
	v_mul_f32_e32 v26, v30, v30
	v_fmac_f32_e32 v26, v34, v34
	v_fmac_f32_e32 v26, v35, v35
	v_fmac_f32_e32 v26, v31, v31
	v_fmac_f32_e32 v26, v36, v36
	v_fmac_f32_e32 v26, v32, v32
	v_fmac_f32_e32 v26, v37, v37
	v_fmac_f32_e32 v26, v33, v33
	v_fmac_f32_e32 v26, v38, v38
	v_fmac_f32_e32 v26, v18, v18
	v_fmac_f32_e32 v26, v39, v39
	v_fmac_f32_e32 v26, v19, v19
	v_fmac_f32_e32 v26, v40, v40
	v_fmac_f32_e32 v26, v20, v20
	v_fmac_f32_e32 v26, v41, v41
	v_fmac_f32_e32 v26, v21, v21
	v_fmac_f32_e32 v26, v42, v42
	v_fmac_f32_e32 v26, v43, v43
	v_fmac_f32_e32 v26, v44, v44
	v_lshlrev_b32_e32 v22, 16, v8
	v_fmac_f32_e32 v26, v45, v45
	v_and_b32_e32 v23, 0xffff0000, v8
	v_fmac_f32_e32 v26, v22, v22
	v_lshlrev_b32_e32 v24, 16, v9
	v_fmac_f32_e32 v26, v23, v23
	v_and_b32_e32 v25, 0xffff0000, v9
	v_fmac_f32_e32 v26, v24, v24
	v_fmac_f32_e32 v26, v25, v25
	v_add_f32_e32 v3, v3, v26
	v_add_f32_e32 v2, v2, v3
	v_add_f32_e32 v2, v5, v2
	v_pk_mul_f32 v[6:7], v[94:95], v[94:95]
	v_add_f32_e32 v2, v4, v2
	v_add_f32_e32 v2, v7, v2
	v_pk_mul_f32 v[8:9], v[100:101], v[100:101]
	v_add_f32_e32 v2, v6, v2
	v_add_f32_e32 v2, v9, v2
	v_add_f32_e32 v2, v8, v2
	ds_bpermute_b32 v3, v171, v2
	s_waitcnt lgkmcnt(0)
	v_add_f32_e32 v2, v2, v3
	ds_bpermute_b32 v3, v199, v2
	s_waitcnt lgkmcnt(0)
	v_add_f32_e32 v2, v2, v3
	v_fmamk_f32 v2, v2, 0x3c000000, v230
	v_mul_f32_e32 v3, 0x4b800000, v2
	v_cmp_gt_f32_e32 vcc, s70, v2
	s_nop 1
	v_cndmask_b32_e32 v2, v2, v3, vcc
	v_rsq_f32_e32 v2, v2
	s_nop 0
	v_mul_f32_e32 v3, 0x45800000, v2
	v_cndmask_b32_e32 v2, v2, v3, vcc
	v_mul_f32_e32 v110, 0x3db504f3, v2
	v_mul_f32_e32 v2, v110, v34
	v_mul_f32_e32 v3, v110, v30
	v_mul_f32_e32 v4, v110, v35
	v_mul_f32_e32 v5, v110, v31
	v_mul_f32_e32 v6, v110, v36
	v_mul_f32_e32 v7, v110, v32
	v_mul_f32_e32 v8, v110, v37
	v_mul_f32_e32 v9, v110, v33
	v_mul_f32_e32 v97, v110, v97
	v_mul_f32_e32 v96, v110, v96
	v_mul_f32_e32 v99, v110, v99
	v_mul_f32_e32 v98, v110, v98
	v_mul_f32_e32 v95, v110, v95
	v_mul_f32_e32 v94, v110, v94
	v_mul_f32_e32 v101, v110, v101
	s_waitcnt vmcnt(1)
	v_mul_f32_e32 v6, v10, v6
	s_waitcnt vmcnt(0)
	v_mul_f32_e32 v2, v14, v2
	v_mul_f32_e32 v3, v15, v3
	v_mul_f32_e32 v4, v16, v4
	v_mul_f32_e32 v5, v17, v5
	v_mul_f32_e32 v7, v11, v7
	v_mul_f32_e32 v8, v12, v8
	v_mul_f32_e32 v9, v13, v9
	v_cvt_pk_bf16_f32 v78, v2, v3
	v_cvt_pk_bf16_f32 v79, v4, v5
	v_cvt_pk_bf16_f32 v80, v6, v7
	v_cvt_pk_bf16_f32 v81, v8, v9
	global_load_dwordx4 v[2:5], v[176:177], off offset:128
	global_load_dwordx4 v[6:9], v[176:177], off offset:144
	v_mul_f32_e32 v14, v110, v40
	v_mul_f32_e32 v15, v110, v20
	v_mul_f32_e32 v16, v110, v41
	v_mul_f32_e32 v17, v110, v21
	v_mul_f32_e32 v10, v110, v38
	v_mul_f32_e32 v11, v110, v18
	v_mul_f32_e32 v12, v110, v39
	v_mul_f32_e32 v13, v110, v19
	v_mul_f32_e32 v18, v110, v23
	v_mul_f32_e32 v19, v110, v24
	v_mul_f32_e32 v20, v110, v25
	v_mul_f32_e32 v100, v110, v100
	s_waitcnt vmcnt(1)
	v_mul_f32_e32 v2, v2, v10
	s_waitcnt vmcnt(0)
	v_mul_f32_e32 v6, v6, v14
	v_mul_f32_e32 v7, v7, v15
	v_mul_f32_e32 v8, v8, v16
	v_mul_f32_e32 v9, v9, v17
	v_mul_f32_e32 v3, v3, v11
	v_mul_f32_e32 v4, v4, v12
	v_mul_f32_e32 v5, v5, v13
	v_cvt_pk_bf16_f32 v82, v2, v3
	v_cvt_pk_bf16_f32 v83, v4, v5
	v_cvt_pk_bf16_f32 v84, v6, v7
	v_cvt_pk_bf16_f32 v85, v8, v9
	global_load_dwordx4 v[6:9], v[176:177], off offset:256
	global_load_dwordx4 v[10:13], v[176:177], off offset:272
	v_mul_f32_e32 v2, v110, v42
	v_mul_f32_e32 v14, v110, v43
	v_mul_f32_e32 v15, v110, v44
	v_mul_f32_e32 v16, v110, v45
	v_mul_f32_e32 v17, v110, v22
	v_mov_b32_e32 v5, 0
	v_mov_b32_e32 v4, v5
	v_mov_b32_e32 v3, v5
	v_mov_b32_e32 v21, v5
	v_mov_b32_e32 v25, v5
	v_mov_b32_e32 v24, v5
	v_mov_b32_e32 v23, v5
	v_mov_b32_e32 v22, v5
	v_mov_b32_e32 v29, v5
	v_mov_b32_e32 v28, v5
	v_mov_b32_e32 v27, v5
	v_mov_b32_e32 v26, v5
	v_mov_b32_e32 v33, v5
	v_mov_b32_e32 v32, v5
	v_mov_b32_e32 v31, v5
	v_mov_b32_e32 v30, v5
	v_mov_b32_e32 v93, v5
	v_mov_b32_e32 v92, v5
	v_mov_b32_e32 v91, v5
	v_mov_b32_e32 v90, v5
	v_mov_b32_e32 v77, v5
	v_mov_b32_e32 v76, v5
	v_mov_b32_e32 v75, v5
	v_mov_b32_e32 v74, v5
	v_mov_b32_e32 v73, v5
	v_mov_b32_e32 v72, v5
	v_mov_b32_e32 v71, v5
	v_mov_b32_e32 v70, v5
	v_mov_b32_e32 v65, v5
	v_mov_b32_e32 v64, v5
	v_mov_b32_e32 v63, v5
	v_mov_b32_e32 v62, v5
	v_mov_b32_e32 v49, v5
	v_mov_b32_e32 v48, v5
	v_mov_b32_e32 v47, v5
	v_mov_b32_e32 v46, v5
	v_mov_b32_e32 v45, v5
	v_mov_b32_e32 v44, v5
	v_mov_b32_e32 v43, v5
	v_mov_b32_e32 v42, v5
	v_mov_b32_e32 v41, v5
	v_mov_b32_e32 v40, v5
	v_mov_b32_e32 v39, v5
	v_mov_b32_e32 v38, v5
	v_mov_b32_e32 v37, v5
	v_mov_b32_e32 v36, v5
	v_mov_b32_e32 v35, v5
	v_mov_b32_e32 v34, v5
	v_mov_b32_e32 v201, v5
	v_mov_b32_e32 v175, v5
	s_waitcnt vmcnt(1)
	v_mul_f32_e32 v2, v2, v6
	v_mul_f32_e32 v6, v14, v7
	v_mul_f32_e32 v7, v15, v8
	v_mul_f32_e32 v8, v16, v9
	s_waitcnt vmcnt(0)
	v_mul_f32_e32 v9, v17, v10
	v_mul_f32_e32 v10, v18, v11
	v_mul_f32_e32 v11, v19, v12
	v_mul_f32_e32 v12, v20, v13
	v_cvt_pk_bf16_f32 v86, v2, v6
	v_cvt_pk_bf16_f32 v87, v7, v8
	v_cvt_pk_bf16_f32 v88, v9, v10
	v_cvt_pk_bf16_f32 v89, v11, v12
	global_load_dwordx4 v[102:105], v[176:177], off offset:400
	global_load_dwordx4 v[106:109], v[176:177], off offset:384
	v_mov_b32_e32 v2, v5
	v_mov_b32_e32 v9, v5
	v_mov_b32_e32 v8, v5
	v_mov_b32_e32 v7, v5
	v_mov_b32_e32 v6, v5
	v_mov_b32_e32 v13, v5
	v_mov_b32_e32 v12, v5
	v_mov_b32_e32 v11, v5
	v_mov_b32_e32 v10, v5
	v_mov_b32_e32 v17, v5
	v_mov_b32_e32 v16, v5
	v_mov_b32_e32 v15, v5
	v_mov_b32_e32 v14, v5
	v_mov_b32_e32 v20, v5
	v_mov_b32_e32 v19, v5
	v_mov_b32_e32 v18, v5
	s_waitcnt vmcnt(1)
	v_mul_f32_e32 v102, v95, v102
	s_waitcnt vmcnt(0)
	v_mul_f32_e32 v97, v97, v108
	v_mul_f32_e32 v96, v96, v109
	v_mul_f32_e32 v99, v99, v106
	v_mul_f32_e32 v98, v98, v107
	v_mul_f32_e32 v103, v94, v103
	v_mul_f32_e32 v101, v101, v104
	v_mul_f32_e32 v100, v100, v105
	v_cvt_pk_bf16_f32 v94, v99, v98
	v_cvt_pk_bf16_f32 v95, v97, v96
	v_cvt_pk_bf16_f32 v96, v102, v103
	v_cvt_pk_bf16_f32 v97, v101, v100
	s_cbranch_scc1 .LBB0_280
	s_bfe_u32 s6, s34, 0x40002
	s_lshl_b32 s7, s6, 1
	v_sub_u32_e64 v2, s7, 4 clamp
	s_and_b32 s10, s26, 48
	v_readfirstlane_b32 s8, v2
	v_sub_u32_e64 v2, s7, 3 clamp
	s_min_u32 s3, s8, 24
	v_readfirstlane_b32 s7, v2
	v_sub_u32_e64 v2, s10, 8 clamp
	v_min_u32_e32 v2, 32, v2
	s_mul_i32 s11, s3, 31
	v_add_u32_e32 v2, s11, v2
	v_add_u32_e32 v2, v2, v173
	v_subrev_u32_e32 v2, s10, v2
	s_mul_i32 s6, s6, 62
	v_subrev_u32_e32 v188, s6, v2
	v_sub_u32_e64 v2, s1, 8 clamp
	s_min_u32 s7, s7, 24
	v_min_u32_e32 v4, 32, v2
	v_or_b32_e32 v2, s1, v192
	s_sub_i32 s6, s7, s3
	v_sub_u32_e64 v2, v2, 8 clamp
	s_add_i32 s6, s6, 15
	s_or_b32 s0, s0, s17
	v_min_u32_e32 v5, 48, v2
	v_or_b32_e32 v2, s13, v192
	s_max_i32 s71, s6, 0
	s_mul_i32 s42, s0, 0x1d1
	v_readlane_b32 s52, v252, 12
	v_mul_u32_u24_e32 v2, 0x4800, v2
	s_lshl_b32 s8, s3, 5
	s_lshl_b32 s9, s7, 5
	s_add_i32 s71, s71, 1
	s_lshl_b64 s[0:1], s[42:43], 2
	v_readlane_b32 s64, v252, 24
	v_lshlrev_b32_e32 v2, 1, v2
	v_mov_b32_e32 v3, v195
	v_readlane_b32 s65, v252, 25
	s_add_u32 s0, s64, s0
	v_lshl_add_u64 v[190:191], v[178:179], 0, v[2:3]
	v_add_u32_e32 v2, v4, v170
	v_add_u32_e32 v3, 16, v5
	s_addc_u32 s1, s65, s1
	v_or_b32_e32 v181, s5, v4
	s_lshl_b32 s10, s4, 8
	v_cmp_ge_u32_e32 vcc, v2, v5
	v_cmp_lt_u32_e64 s[4:5], v2, v3
	v_or_b32_e32 v4, 1, v2
	v_readlane_b32 s53, v252, 13
	s_and_b64 s[40:41], vcc, s[4:5]
	v_cmp_ge_u32_e32 vcc, v4, v5
	v_cmp_lt_u32_e64 s[4:5], v4, v3
	v_or_b32_e32 v4, 2, v2
	v_readlane_b32 s54, v252, 14
	v_readlane_b32 s55, v252, 15
	s_and_b64 s[52:53], vcc, s[4:5]
	v_cmp_ge_u32_e32 vcc, v4, v5
	v_cmp_lt_u32_e64 s[4:5], v4, v3
	v_or_b32_e32 v4, 3, v2
	v_readlane_b32 s60, v252, 20
	v_readlane_b32 s61, v252, 21
	s_and_b64 s[54:55], vcc, s[4:5]
	v_cmp_ge_u32_e32 vcc, v4, v5
	v_cmp_lt_u32_e64 s[4:5], v4, v3
	v_or_b32_e32 v4, 4, v2
	v_readlane_b32 s62, v252, 22
	v_readlane_b32 s63, v252, 23
	s_and_b64 s[60:61], vcc, s[4:5]
	v_cmp_ge_u32_e32 vcc, v4, v5
	v_cmp_lt_u32_e64 s[4:5], v4, v3
	v_or_b32_e32 v4, 5, v2
	s_and_b64 s[62:63], vcc, s[4:5]
	v_cmp_ge_u32_e32 vcc, v4, v5
	v_cmp_lt_u32_e64 s[4:5], v4, v3
	v_or_b32_e32 v4, 6, v2
	s_and_b64 s[80:81], vcc, s[4:5]
	v_cmp_ge_u32_e32 vcc, v4, v5
	v_cmp_lt_u32_e64 s[4:5], v4, v3
	v_or_b32_e32 v2, 7, v2
	s_and_b64 s[82:83], vcc, s[4:5]
	v_cmp_ge_u32_e32 vcc, v2, v5
	v_cmp_lt_u32_e64 s[4:5], v2, v3
	s_add_i32 s10, s10, s8
	s_and_b64 s[6:7], vcc, s[4:5]
	s_sub_i32 s4, s10, s9
	v_mov_b32_e32 v175, 0
	s_mov_b32 s70, 0
	s_add_i32 s78, s4, 0x3f00
	v_mov_b32_e32 v253, 0xff800000
	s_movk_i32 s22, 0x1d0
	v_mov_b32_e32 v185, 0xff800000
	v_mov_b32_e32 v203, 0xff800000
	v_mov_b32_e32 v201, 0
	v_mov_b32_e32 v34, 0
	v_mov_b32_e32 v35, v175
	v_mov_b32_e32 v36, v175
	v_mov_b32_e32 v37, v175
	v_mov_b32_e32 v38, 0
	v_mov_b32_e32 v39, v175
	v_mov_b32_e32 v40, v175
	v_mov_b32_e32 v41, v175
	v_mov_b32_e32 v42, 0
	v_mov_b32_e32 v43, v175
	v_mov_b32_e32 v44, v175
	v_mov_b32_e32 v45, v175
	v_mov_b32_e32 v46, 0
	v_mov_b32_e32 v47, v175
	v_mov_b32_e32 v48, v175
	v_mov_b32_e32 v49, v175
	v_mov_b32_e32 v62, 0
	v_mov_b32_e32 v63, v175
	v_mov_b32_e32 v64, v175
	v_mov_b32_e32 v65, v175
	v_mov_b32_e32 v70, 0
	v_mov_b32_e32 v71, v175
	v_mov_b32_e32 v72, v175
	v_mov_b32_e32 v73, v175
	v_mov_b32_e32 v74, 0
	v_mov_b32_e32 v75, v175
	v_mov_b32_e32 v76, v175
	v_mov_b32_e32 v77, v175
	v_mov_b32_e32 v90, 0
	v_mov_b32_e32 v91, v175
	v_mov_b32_e32 v92, v175
	v_mov_b32_e32 v93, v175
	v_mov_b32_e32 v30, 0
	v_mov_b32_e32 v31, v175
	v_mov_b32_e32 v32, v175
	v_mov_b32_e32 v33, v175
	v_mov_b32_e32 v26, 0
	v_mov_b32_e32 v27, v175
	v_mov_b32_e32 v28, v175
	v_mov_b32_e32 v29, v175
	v_mov_b32_e32 v22, 0
	v_mov_b32_e32 v23, v175
	v_mov_b32_e32 v24, v175
	v_mov_b32_e32 v25, v175
	v_mov_b32_e32 v18, 0
	v_mov_b32_e32 v19, v175
	v_mov_b32_e32 v20, v175
	v_mov_b32_e32 v21, v175
	v_mov_b32_e32 v14, 0
	v_mov_b32_e32 v15, v175
	v_mov_b32_e32 v16, v175
	v_mov_b32_e32 v17, v175
	v_mov_b32_e32 v10, 0
	v_mov_b32_e32 v11, v175
	v_mov_b32_e32 v12, v175
	v_mov_b32_e32 v13, v175
	v_mov_b32_e32 v6, 0
	v_mov_b32_e32 v7, v175
	v_mov_b32_e32 v8, v175
	v_mov_b32_e32 v9, v175
	v_mov_b32_e32 v2, 0
	v_mov_b32_e32 v3, v175
	v_mov_b32_e32 v4, v175
	v_mov_b32_e32 v5, v175
	v_readlane_b32 s56, v252, 16
	v_readlane_b32 s57, v252, 17
	v_readlane_b32 s58, v252, 18
	v_readlane_b32 s59, v252, 19
	v_readlane_b32 s66, v252, 26
	v_readlane_b32 s67, v252, 27
	s_branch .LBB0_286

.LBB0_288:
	v_ashrrev_i32_e32 v131, 31, v130
	v_lshl_add_u64 v[98:99], v[130:131], 1, v[190:191]
	v_add_co_u32_e32 v100, vcc, 0x90000, v98
	s_waitcnt vmcnt(0)
	v_add_u32_e32 v148, v130, v193
	v_addc_co_u32_e32 v101, vcc, 0, v99, vcc
	s_cmp_lt_i32 s70, s2
	s_cbranch_scc0 .Lattn_nobias
	v_add_u32_e32 v242, 8, v188
	v_add_u32_e32 v243, 9, v188
	v_add_u32_e32 v244, 10, v188
	v_add_u32_e32 v245, 11, v188
	v_add_u32_e32 v246, 12, v188
	v_add_u32_e32 v247, 13, v188
	v_add_u32_e32 v248, 14, v188
	v_add_u32_e32 v249, 15, v188
	v_med3_i32 v242, v242, 0, s22
	v_med3_i32 v243, v243, 0, s22
	v_med3_i32 v244, v244, 0, s22
	v_med3_i32 v245, v245, 0, s22
	v_med3_i32 v246, v246, 0, s22
	v_med3_i32 v247, v247, 0, s22
	v_med3_i32 v248, v248, 0, s22
	v_med3_i32 v249, v249, 0, s22
	v_lshlrev_b32_e32 v242, 2, v242
	v_lshlrev_b32_e32 v243, 2, v243
	v_lshlrev_b32_e32 v244, 2, v244
	v_lshlrev_b32_e32 v245, 2, v245
	v_lshlrev_b32_e32 v246, 2, v246
	v_lshlrev_b32_e32 v247, 2, v247
	v_lshlrev_b32_e32 v248, 2, v248
	v_lshlrev_b32_e32 v249, 2, v249
	global_load_dword v213, v242, s[0:1]
	global_load_dword v214, v243, s[0:1]
	global_load_dword v215, v244, s[0:1]
	global_load_dword v216, v245, s[0:1]
	global_load_dword v217, v246, s[0:1]
	global_load_dword v218, v247, s[0:1]
	global_load_dword v219, v248, s[0:1]
	global_load_dword v220, v249, s[0:1]
	v_subrev_u32_e32 v242, 23, v188
	v_subrev_u32_e32 v243, 22, v188
	v_subrev_u32_e32 v244, 21, v188
	v_subrev_u32_e32 v245, 20, v188
	v_subrev_u32_e32 v246, 19, v188
	v_subrev_u32_e32 v247, 18, v188
	v_subrev_u32_e32 v248, 17, v188
	v_subrev_u32_e32 v249, 16, v188
	v_med3_i32 v242, v242, 0, s22
	v_med3_i32 v243, v243, 0, s22
	v_med3_i32 v244, v244, 0, s22
	v_med3_i32 v245, v245, 0, s22
	v_med3_i32 v246, v246, 0, s22
	v_med3_i32 v247, v247, 0, s22
	v_med3_i32 v248, v248, 0, s22
	v_med3_i32 v249, v249, 0, s22
	v_lshlrev_b32_e32 v242, 2, v242
	v_lshlrev_b32_e32 v243, 2, v243
	v_lshlrev_b32_e32 v244, 2, v244
	v_lshlrev_b32_e32 v245, 2, v245
	v_lshlrev_b32_e32 v246, 2, v246
	v_lshlrev_b32_e32 v247, 2, v247
	v_lshlrev_b32_e32 v248, 2, v248
	v_lshlrev_b32_e32 v249, 2, v249
	global_load_dword v221, v242, s[0:1]
	global_load_dword v222, v243, s[0:1]
	global_load_dword v223, v244, s[0:1]
	global_load_dword v224, v245, s[0:1]
	global_load_dword v225, v246, s[0:1]
	global_load_dword v226, v247, s[0:1]
	global_load_dword v227, v248, s[0:1]
	global_load_dword v228, v249, s[0:1]
.Lattn_nobias:
	global_load_dwordx4 v[126:129], v[98:99], off
	global_load_dwordx4 v[122:125], v[100:101], off
	v_add_co_u32_e32 v100, vcc, 0x120000, v98
	v_mov_b64_e32 v[146:147], s[50:51]
	s_nop 0
	v_addc_co_u32_e32 v101, vcc, 0, v99, vcc
	v_add_co_u32_e32 v102, vcc, 0x1b0000, v98
	v_mad_i64_i32 v[130:131], s[10:11], v148, s37, v[146:147]
	s_nop 0
	v_addc_co_u32_e32 v103, vcc, 0, v99, vcc
	global_load_dwordx4 v[118:121], v[100:101], off
	global_load_dwordx4 v[114:117], v[102:103], off
	v_add_co_u32_e32 v100, vcc, 0x240000, v98
	s_lshl_b32 s42, s13, 1
	s_nop 0
	v_addc_co_u32_e32 v101, vcc, 0, v99, vcc
	v_add_co_u32_e32 v102, vcc, 0x2d0000, v98
	v_lshl_add_u64 v[130:131], v[130:131], 0, s[42:43]
	s_nop 0
	v_addc_co_u32_e32 v103, vcc, 0, v99, vcc
	global_load_dwordx4 v[110:113], v[100:101], off
	global_load_dwordx4 v[106:109], v[102:103], off
	v_add_co_u32_e32 v100, vcc, 0x360000, v98
	v_add_u32_e32 v148, 4, v148
	s_nop 0
	v_addc_co_u32_e32 v101, vcc, 0, v99, vcc
	v_add_co_u32_e32 v98, vcc, 0x3f0000, v98
	v_lshl_add_u64 v[130:131], v[130:131], 0, v[194:195]
	s_nop 0
	v_addc_co_u32_e32 v99, vcc, 0, v99, vcc
	v_mad_i64_i32 v[146:147], s[10:11], v148, s37, v[146:147]
	v_add_co_u32_e32 v140, vcc, s91, v130
	v_lshl_add_u64 v[146:147], v[146:147], 0, s[42:43]
	s_nop 0
	v_addc_co_u32_e32 v141, vcc, 0, v131, vcc
	v_lshl_add_u64 v[146:147], v[146:147], 0, v[194:195]
	v_lshl_add_u64 v[148:149], v[146:147], 0, s[68:69]
	v_add_co_u32_e32 v146, vcc, 0x2000, v146
	v_lshl_add_u64 v[138:139], v[130:131], 0, s[68:69]
	s_nop 0
	v_addc_co_u32_e32 v147, vcc, 0, v147, vcc
	global_load_dwordx4 v[102:105], v[100:101], off
	s_nop 0
	global_load_dwordx4 v[98:101], v[98:99], off
	s_nop 0
	global_load_dwordx4 v[130:133], v[138:139], off offset:64
	global_load_dwordx4 v[134:137], v[138:139], off offset:128
	global_load_dwordx4 v[142:145], v[140:141], off offset:2048
	s_nop 0
	global_load_dwordx4 v[138:141], v[138:139], off offset:192
	s_nop 0
	global_load_dwordx4 v[150:153], v[148:149], off offset:64
	global_load_dwordx4 v[154:157], v[148:149], off offset:128
	global_load_dwordx4 v[158:161], v[146:147], off offset:2048
	s_nop 0
	global_load_dwordx4 v[146:149], v[148:149], off offset:192
	s_cmp_lt_u32 s70, 8
	s_cselect_b64 s[10:11], -1, 0
	s_or_b64 s[10:11], s[8:9], s[10:11]
	v_cndmask_b32_e64 v162, 0, 1, s[4:5]
	s_andn2_b64 vcc, exec, s[10:11]
	v_cmp_ne_u32_e64 s[4:5], 1, v162
	s_cbranch_vccnz .LBB0_309
	s_waitcnt vmcnt(5)
	v_mfma_f32_16x16x32_bf16 v[162:165], v[142:145], v[50:53], 0
	s_and_b64 vcc, exec, s[4:5]
	v_mfma_f32_16x16x32_bf16 v[162:165], v[130:133], v[54:57], v[162:165]
	v_mfma_f32_16x16x32_bf16 v[162:165], v[134:137], v[58:61], v[162:165]
	s_waitcnt vmcnt(4)
	v_mfma_f32_16x16x32_bf16 v[166:169], v[138:141], v[66:69], v[162:165]
	s_waitcnt vmcnt(1)
	v_mfma_f32_16x16x32_bf16 v[162:165], v[158:161], v[50:53], 0
	v_mfma_f32_16x16x32_bf16 v[162:165], v[150:153], v[54:57], v[162:165]
	v_mfma_f32_16x16x32_bf16 v[162:165], v[154:157], v[58:61], v[162:165]
	s_waitcnt vmcnt(0)
	v_mfma_f32_16x16x32_bf16 v[162:165], v[146:149], v[66:69], v[162:165]
	s_cbranch_vccnz .LBB0_307
	s_nop 7
	v_add_f32_e32 v208, v166, v213
	v_add_f32_e32 v206, v167, v214
	v_add_f32_e32 v209, v168, v215
	v_add_f32_e32 v207, v169, v216
	v_add_f32_e32 v211, v162, v217
	v_add_f32_e32 v210, v163, v218
	v_add_f32_e32 v212, v164, v219
	v_add_f32_e32 v189, v165, v220
	v_cndmask_b32_e64 v208, v253, v208, s[40:41]
	v_cndmask_b32_e64 v206, v253, v206, s[52:53]
	v_cndmask_b32_e64 v209, v253, v209, s[54:55]
	v_cndmask_b32_e64 v207, v253, v207, s[60:61]
	v_cndmask_b32_e64 v211, v253, v211, s[62:63]
	v_cndmask_b32_e64 v210, v253, v210, s[80:81]
	v_cndmask_b32_e64 v212, v253, v212, s[82:83]
	v_cndmask_b32_e64 v189, v253, v189, s[6:7]
	s_branch .LBB0_308

.LBB0_309:
	s_add_i32 s10, s3, s70
	s_cmp_ge_u32 s10, s14
	s_cselect_b64 s[10:11], -1, 0
	s_or_b64 s[8:9], s[8:9], s[10:11]
	s_andn2_b64 vcc, exec, s[8:9]
	s_cbranch_vccnz .LBB0_285
	s_waitcnt vmcnt(5)
	v_mfma_f32_16x16x32_bf16 v[142:145], v[142:145], v[78:81], 0
	s_and_b64 vcc, exec, s[4:5]
	v_mfma_f32_16x16x32_bf16 v[130:133], v[130:133], v[82:85], v[142:145]
	v_mfma_f32_16x16x32_bf16 v[130:133], v[134:137], v[86:89], v[130:133]
	s_waitcnt vmcnt(4)
	v_mfma_f32_16x16x32_bf16 v[134:137], v[138:141], v[94:97], v[130:133]
	s_waitcnt vmcnt(1)
	v_mfma_f32_16x16x32_bf16 v[130:133], v[158:161], v[78:81], 0
	v_mfma_f32_16x16x32_bf16 v[130:133], v[150:153], v[82:85], v[130:133]
	v_mfma_f32_16x16x32_bf16 v[130:133], v[154:157], v[86:89], v[130:133]
	s_waitcnt vmcnt(0)
	v_mfma_f32_16x16x32_bf16 v[130:133], v[146:149], v[94:97], v[130:133]
	s_cbranch_vccnz .LBB0_327
	s_nop 7
	v_add_f32_e32 v140, v134, v221
	v_add_f32_e32 v138, v135, v222
	v_add_f32_e32 v141, v136, v223
	v_add_f32_e32 v139, v137, v224
	v_add_f32_e32 v143, v130, v225
	v_add_f32_e32 v142, v131, v226
	v_add_f32_e32 v145, v132, v227
	v_add_f32_e32 v144, v133, v228
	v_cndmask_b32_e64 v140, v253, v140, s[40:41]
	v_cndmask_b32_e64 v138, v253, v138, s[52:53]
	v_cndmask_b32_e64 v141, v253, v141, s[54:55]
	v_cndmask_b32_e64 v139, v253, v139, s[60:61]
	v_cndmask_b32_e64 v143, v253, v143, s[62:63]
	v_cndmask_b32_e64 v142, v253, v142, s[80:81]
	v_cndmask_b32_e64 v145, v253, v145, s[82:83]
	v_cndmask_b32_e64 v144, v253, v144, s[6:7]
	s_branch .LBB0_284

	.amdhsa_kernel _Z14fwd_megakernel6Params
		.amdhsa_group_segment_fixed_size 131104
		.amdhsa_private_segment_fixed_size 0
		.amdhsa_kernarg_size 424
		.amdhsa_user_sgpr_count 2
		.amdhsa_user_sgpr_dispatch_ptr 0
		.amdhsa_user_sgpr_queue_ptr 0
		.amdhsa_user_sgpr_kernarg_segment_ptr 1
		.amdhsa_user_sgpr_dispatch_id 0
		.amdhsa_user_sgpr_kernarg_preload_length 0
		.amdhsa_user_sgpr_kernarg_preload_offset 0
		.amdhsa_user_sgpr_private_segment_size 0
		.amdhsa_uses_dynamic_stack 0
		.amdhsa_enable_private_segment 0
		.amdhsa_system_sgpr_workgroup_id_x 1
		.amdhsa_system_sgpr_workgroup_id_y 0
		.amdhsa_system_sgpr_workgroup_id_z 0
		.amdhsa_system_sgpr_workgroup_info 0
		.amdhsa_system_vgpr_workitem_id 2
		.amdhsa_next_free_vgpr 256
		.amdhsa_next_free_sgpr 102
		.amdhsa_accum_offset 256
		.amdhsa_reserve_vcc 1
		.amdhsa_float_round_mode_32 0
		.amdhsa_float_round_mode_16_64 0
		.amdhsa_float_denorm_mode_32 3
		.amdhsa_float_denorm_mode_16_64 3
		.amdhsa_dx10_clamp 1
		.amdhsa_ieee_mode 1
		.amdhsa_fp16_overflow 0
		.amdhsa_tg_split 0
		.amdhsa_exception_fp_ieee_invalid_op 0
		.amdhsa_exception_fp_denorm_src 0
		.amdhsa_exception_fp_ieee_div_zero 0
		.amdhsa_exception_fp_ieee_overflow 0
		.amdhsa_exception_fp_ieee_underflow 0
		.amdhsa_exception_fp_ieee_inexact 0
		.amdhsa_exception_int_div_zero 0
	.end_amdhsa_kernel

amdhsa.kernels:
  - .agpr_count:     0
    .args:
      - .offset:         0
        .size:           168
        .value_kind:     by_value
      - .offset:         168
        .size:           4
        .value_kind:     hidden_block_count_x
      - .offset:         172
        .size:           4
        .value_kind:     hidden_block_count_y
      - .offset:         176
        .size:           4
        .value_kind:     hidden_block_count_z
      - .offset:         180
        .size:           2
        .value_kind:     hidden_group_size_x
      - .offset:         182
        .size:           2
        .value_kind:     hidden_group_size_y
      - .offset:         184
        .size:           2
        .value_kind:     hidden_group_size_z
      - .offset:         186
        .size:           2
        .value_kind:     hidden_remainder_x
      - .offset:         188
        .size:           2
        .value_kind:     hidden_remainder_y
      - .offset:         190
        .size:           2
        .value_kind:     hidden_remainder_z
      - .offset:         208
        .size:           8
        .value_kind:     hidden_global_offset_x
      - .offset:         216
        .size:           8
        .value_kind:     hidden_global_offset_y
      - .offset:         224
        .size:           8
        .value_kind:     hidden_global_offset_z
      - .offset:         232
        .size:           2
        .value_kind:     hidden_grid_dims
      - .offset:         256
        .size:           8
        .value_kind:     hidden_multigrid_sync_arg
    .group_segment_fixed_size: 131104
    .kernarg_segment_align: 8
    .kernarg_segment_size: 424
    .language:       OpenCL C
    .language_version:
      - 2
      - 0
    .max_flat_workgroup_size: 512
    .name:           _Z14fwd_megakernel6Params
    .private_segment_fixed_size: 0
    .sgpr_count:     108
    .sgpr_spill_count: 160
    .symbol:         _Z14fwd_megakernel6Params.kd
    .uniform_work_group_size: 1
    .uses_dynamic_stack: false
    .vgpr_count:     256
    .vgpr_spill_count: 0
    .wavefront_size: 64
